# v25: v24 + RG-LRU conv loop rewritten (8 LDS reads batched, one wait, fma chain per token, state rows stored after the loop)
# speedup vs baseline: 1.0213x; 1.0088x over previous
; DI float bf2f(unsigned v) { return __uint_as_float(v << 16); }
; DI bf16_t f2bf(float f) { return (bf16_t)(cvt_pk(f, 0.f) & 0xffffu); }
; #define LDS_WAIT() asm volatile("s_waitcnt lgkmcnt(0)" ::: "memory")
; template <bool FINAL>
; DI void lru_unit(KA a, int l, int unit, LAS unsigned char* lds) {
;     ...
;     {
;         const int ch = 64 * w + lane;
;         const float* cw = a->in[11] + (size_t)l * 4 * DLRU;
;         const float cw0 = cw[ch], cw1 = cw[DLRU + ch], cw2 = cw[2 * DLRU + ch], cw3 = cw[3 * DLRU + ch], cb = a->in[12][l * DLRU + ch];
;         float xm3 = 0.f, xm2 = 0.f, xm1 = 0.f;
;         if (u.prompt) { if (u.c > 0) { xm3 = bf2f(U[(size_t)(row0 - 3) * UN + ch]); xm2 = bf2f(U[(size_t)(row0 - 2) * UN + ch]); xm1 = bf2f(U[(size_t)(row0 - 1) * UN + ch]); } }
;         else { const float* cs = a->in[3] + ((size_t)(l * NSB + u.s) * 3) * DLRU + ch; xm3 = cs[0]; xm2 = cs[DLRU]; xm1 = cs[2 * DLRU]; }
;         float* cout = out + (u.prompt ? O_CP + (size_t)(l * NB + u.b) * 3 * DLRU : O_CS + (size_t)(l * NSB + u.s) * 3 * DLRU) + ch;
;         LDS_WAIT(); asm volatile("" ::: "memory");
; #pragma unroll 8
;         for (int t = 0; t < 64; ++t) {
;             const float xv = bf2f(xr[t * 64 + lane]);
;             const float xcv = cb + cw0 * xm3 + cw1 * xm2 + cw2 * xm1 + cw3 * xv;
;             xc[t * 72 + lane] = (t < nvalid) ? f2bf(xcv) : (bf16_t)0;
;             xm3 = xm2; xm2 = xm1; xm1 = xv;
;             if (FINAL && lastc && t >= nvalid - 3 && t < nvalid) cout[(size_t)(t - (nvalid - 3)) * DLRU] = xv;
;         }
;     }
;     LDS_WAIT(); asm volatile("" ::: "memory");
;     const int taur = 16 * ((r >> 2) & 1) + 4 * (r >> 3) + (r & 3);
;     bf16x8 fa[4], fx[4];
; #pragma unroll
;     for (int ks = 0; ks < 4; ++ks) { fa[ks] = *(const bf16x8*)(WaT + r * 64 + ks * 16 + 8 * h); fx[ks] = *(const bf16x8*)(WxT + r * 64 + ks * 16 + 8 * h); }
.LBB0_967:
	v_readlane_b32 s20, v255, 14
	v_readlane_b32 s21, v255, 15
	s_xor_b64 s[8:9], s[20:21], -1
	s_cmp_eq_u32 s94, 32
	s_cselect_b64 s[14:15], -1, 0
	s_add_i32 s18, s0, s60
	v_readlane_b32 s0, v255, 9
	s_mul_i32 s7, s10, 0x2400
	s_add_i32 s16, s12, s0
	s_add_i32 s95, s7, 0
	s_or_b64 s[14:15], s[8:9], s[14:15]
	s_ashr_i32 s17, s16, 31
	s_load_dwordx4 s[24:27], s[2:3], 0xd0
	s_and_b64 s[8:9], s[20:21], exec
	s_cselect_b32 s0, s16, s18
	s_cselect_b32 s7, s17, 0
	s_mulk_i32 s7, 0x1800
	s_mul_hi_u32 s8, s0, 0x1800
	s_add_i32 s8, s8, s7
	s_mulk_i32 s0, 0x1800
	s_waitcnt lgkmcnt(0)
	s_add_u32 s0, s24, s0
	s_addc_u32 s7, s25, s8
	s_lshl_b32 s6, s6, 2
	s_waitcnt lgkmcnt(0)
	s_add_u32 s6, s0, s6
	s_addc_u32 s7, s7, 0
	s_mov_b32 s19, s1
	v_lshl_add_u64 v[4:5], v[4:5], 2, s[6:7]
	s_add_i32 s20, s88, -3
	s_xor_b64 s[6:7], s[14:15], -1
	v_lshlrev_b32_e32 v15, 1, v32
	s_mov_b32 s24, 0
	s_sub_i32 s21, 0, s88
	s_mov_b32 s23, s95
	s_waitcnt vmcnt(0)
	v_mov_b32_e32 v8, v9
	v_add_u32_e32 v17, s11, v15
	v_add_u32_e32 v17, 0x12000, v17
	v_add_u32_e32 v16, s23, v15
.Llru_conv_loop:
	ds_read_u16 v20, v17
	ds_read_u16 v21, v17 offset:128
	ds_read_u16 v22, v17 offset:256
	ds_read_u16 v23, v17 offset:384
	ds_read_u16 v24, v17 offset:512
	ds_read_u16 v25, v17 offset:640
	ds_read_u16 v26, v17 offset:768
	ds_read_u16 v27, v17 offset:896
	s_waitcnt lgkmcnt(0)
	v_lshlrev_b32_e32 v20, 16, v20
	v_lshlrev_b32_e32 v21, 16, v21
	v_lshlrev_b32_e32 v22, 16, v22
	v_lshlrev_b32_e32 v23, 16, v23
	v_lshlrev_b32_e32 v24, 16, v24
	v_lshlrev_b32_e32 v25, 16, v25
	v_lshlrev_b32_e32 v26, 16, v26
	v_lshlrev_b32_e32 v27, 16, v27
	v_fma_f32 v10, v0, v6, v14
	v_fma_f32 v11, v0, v7, v14
	v_fmac_f32_e32 v10, v1, v7
	v_fmac_f32_e32 v11, v1, v8
	v_fmac_f32_e32 v10, v2, v8
	v_fmac_f32_e32 v11, v2, v20
	v_fmac_f32_e32 v10, v3, v20
	v_fmac_f32_e32 v11, v3, v21
	v_cvt_pk_bf16_f32 v10, v10, v145
	v_cvt_pk_bf16_f32 v11, v11, v145
	ds_write_b16 v16, v10
	ds_write_b16 v16, v11 offset:144
	v_fma_f32 v10, v0, v8, v14
	v_fma_f32 v11, v0, v20, v14
	v_fmac_f32_e32 v10, v1, v20
	v_fmac_f32_e32 v11, v1, v21
	v_fmac_f32_e32 v10, v2, v21
	v_fmac_f32_e32 v11, v2, v22
	v_fmac_f32_e32 v10, v3, v22
	v_fmac_f32_e32 v11, v3, v23
	v_cvt_pk_bf16_f32 v10, v10, v145
	v_cvt_pk_bf16_f32 v11, v11, v145
	ds_write_b16 v16, v10 offset:288
	ds_write_b16 v16, v11 offset:432
	v_fma_f32 v10, v0, v21, v14
	v_fma_f32 v11, v0, v22, v14
	v_fmac_f32_e32 v10, v1, v22
	v_fmac_f32_e32 v11, v1, v23
	v_fmac_f32_e32 v10, v2, v23
	v_fmac_f32_e32 v11, v2, v24
	v_fmac_f32_e32 v10, v3, v24
	v_fmac_f32_e32 v11, v3, v25
	v_cvt_pk_bf16_f32 v10, v10, v145
	v_cvt_pk_bf16_f32 v11, v11, v145
	ds_write_b16 v16, v10 offset:576
	ds_write_b16 v16, v11 offset:720
	v_fma_f32 v10, v0, v23, v14
	v_fma_f32 v11, v0, v24, v14
	v_fmac_f32_e32 v10, v1, v24
	v_fmac_f32_e32 v11, v1, v25
	v_fmac_f32_e32 v10, v2, v25
	v_fmac_f32_e32 v11, v2, v26
	v_fmac_f32_e32 v10, v3, v26
	v_fmac_f32_e32 v11, v3, v27
	v_cvt_pk_bf16_f32 v10, v10, v145
	v_cvt_pk_bf16_f32 v11, v11, v145
	ds_write_b16 v16, v10 offset:864
	ds_write_b16 v16, v11 offset:1008
	v_mov_b32_e32 v6, v25
	v_mov_b32_e32 v7, v26
	v_mov_b32_e32 v8, v27
	v_add_u32_e32 v17, 0x400, v17
	v_add_u32_e32 v16, 0x480, v16
	s_add_i32 s24, s24, 8
	s_cmp_lt_u32 s24, s88
	s_cbranch_scc1 .Llru_conv_loop
	s_and_b64 vcc, exec, s[6:7]
	s_cbranch_vccnz .Llru_conv_done
	global_store_dword v[4:5], v6, off
	global_store_dword v[4:5], v7, off offset:2048
	s_mov_b64 s[8:9], 0x1000
	v_lshl_add_u64 v[10:11], v[4:5], 0, s[8:9]
	global_store_dword v[10:11], v8, off
.Llru_conv_done:
.LBB0_1001:
	s_ashr_i32 s11, s10, 31
	v_readlane_b32 s0, v255, 7
	s_add_u32 s6, s10, s0
	s_load_dwordx4 s[24:27], s[2:3], 0xd0
	s_addc_u32 s7, s11, 0
	s_lshl_b64 s[6:7], s[6:7], 13
	v_readlane_b32 s0, v255, 8
	s_add_u32 s8, s10, s0
	s_addc_u32 s9, s11, 0
	s_lshl_b64 s[8:9], s[8:9], 13
	s_waitcnt lgkmcnt(0)
	s_mov_b64 s[30:31], s[26:27]
	s_add_u32 s0, s30, 0x180000
	s_addc_u32 s20, s31, 0
	s_add_u32 s6, s0, s6
	s_addc_u32 s7, s20, s7
	v_and_b32_e32 v124, 31, v35
	v_lshrrev_b32_e32 v8, 5, v32
	s_mov_b64 s[28:29], s[24:25]
	s_add_u32 s24, s0, s8
	v_lshrrev_b32_e32 v0, 1, v35
	v_lshlrev_b32_e32 v144, 7, v124
	s_addc_u32 s25, s20, s9
	s_waitcnt lgkmcnt(0)
	v_and_b32_e32 v7, 12, v0
	v_lshl_add_u64 v[2:3], s[6:7], 0, v[144:145]
	v_lshlrev_b32_e32 v0, 4, v8
	v_mov_b32_e32 v1, v145
	v_lshl_add_u64 v[2:3], v[2:3], 0, v[0:1]
	v_lshl_add_u64 v[4:5], s[24:25], 0, v[144:145]
	v_lshl_add_u64 v[4:5], v[4:5], 0, v[0:1]
	global_load_dwordx4 v[64:67], v[2:3], off
	global_load_dwordx4 v[68:71], v[4:5], off
	global_load_dwordx4 v[72:75], v[2:3], off offset:32
	global_load_dwordx4 v[76:79], v[4:5], off offset:32
	global_load_dwordx4 v[80:83], v[2:3], off offset:64
	global_load_dwordx4 v[84:87], v[4:5], off offset:64
	global_load_dwordx4 v[88:91], v[2:3], off offset:96
	global_load_dwordx4 v[92:95], v[4:5], off offset:96
	v_lshlrev_b32_e32 v6, 2, v35
	v_and_b32_e32 v9, 3, v35
	v_and_b32_e32 v2, 16, v6
	v_lshrrev_b32_e32 v10, 2, v32
	v_or3_b32 v9, v7, v9, v2
	v_add_u32_e32 v2, s13, v10
	v_mov_b64_e32 v[4:5], s[4:5]
	v_mad_i64_i32 v[4:5], s[4:5], v2, s64, v[4:5]
	v_readlane_b32 s4, v255, 18
	v_readlane_b32 s5, v255, 19
	s_lshl_b64 s[20:21], s[4:5], 1
	v_and_b32_e32 v11, 24, v34
	v_lshl_add_u64 v[4:5], v[4:5], 0, s[20:21]
	v_lshlrev_b32_e32 v6, 1, v11
	v_mov_b32_e32 v7, v145
	s_lshl_b64 s[4:5], s[18:19], 11
	v_lshl_add_u64 v[112:113], v[4:5], 0, v[6:7]
	v_and_b32_e32 v5, 64, v221
	v_writelane_b32 v255, s4, 20
	v_xor_b32_e32 v4, 32, v221
	v_add_u32_e32 v5, 64, v5
	v_writelane_b32 v255, s5, 21
	s_add_u32 s4, s30, 0x8000
	v_cmp_lt_i32_e32 vcc, v4, v5
	s_addc_u32 s5, s31, 0
; template <bool FINAL>
; DI void lru_unit(KA a, int l, int unit, LAS unsigned char* lds) {
;     ...
;                 unsigned long long* ls = (unsigned long long*)(a->ws + WS_LSUM);
;                 unsigned* lf = (unsigned*)(a->ws + WS_LFLAG);
;                 const unsigned epoch = (unsigned)l + 1u;
;                 if (u.c < NCH - 1) {
;                     const float Pt = P0 * P1 * P2 * P3, Ht = ((H0 * P1 + H1) * P2 + H2) * P3 + H3;
;                     if (h == 0) __hip_atomic_store(ls + (size_t)unit * DLRU + chn, (unsigned long long)__float_as_uint(Pt) | ((unsigned long long)__float_as_uint(Ht) << 32), __ATOMIC_RELAXED, __HIP_MEMORY_SCOPE_AGENT);
;                     asm volatile("s_waitcnt vmcnt(0)" ::: "memory");
;                     if (lane == 0) __hip_atomic_store(lf + ((size_t)unit * 8 + w) * 2 + nb, epoch, __ATOMIC_RELAXED, __HIP_MEMORY_SCOPE_AGENT);
;                 }
;                 if (u.c > 0) {
;                     {
;                         const unsigned* fp = lf + ((size_t)(u.b * NCH + (lane < u.c ? lane : 0)) * 8 + w) * 2 + nb;
;                         unsigned sp = 0;
;                         for (;;) {
;                             const bool ok = (lane >= u.c) || (__hip_atomic_load(fp, __ATOMIC_RELAXED, __HIP_MEMORY_SCOPE_AGENT) == epoch);
;                             if (__all(ok)) break;
;                             __builtin_amdgcn_s_sleep(2);
;                             if (++sp > (1u << 22)) break;
;                         }
;                     }
;                     const unsigned long long* lp = ls + (size_t)(u.b * NCH) * DLRU + chn;
;                     for (int c0 = 0; c0 < u.c; c0 += 8) {
;                         unsigned long long pv[8];
; #pragma unroll
;                         for (int k = 0; k < 8; ++k) { pv[k] = 0x3f800000ull; if (c0 + k < u.c) pv[k] = __hip_atomic_load(lp + (size_t)(c0 + k) * DLRU, __ATOMIC_RELAXED, __HIP_MEMORY_SCOPE_AGENT); }
; #pragma unroll
;                         for (int k = 0; k < 8; ++k) cin = __uint_as_float((unsigned)pv[k]) * cin + __uint_as_float((unsigned)(pv[k] >> 32));
;                     }
;                 }
;             }
;             const float c1 = P0 * cin + H0, c2 = P1 * c1 + H1, c3 = P2 * c2 + H2;
;             const float cA = h ? c1 : cin, cB = h ? c3 : c2;
;             bf16_t* Y = (bf16_t*)(a->ws + WS_Y);
	v_or_b32_e32 v144, 0x1000, v144
	v_cndmask_b32_e32 v4, v221, v4, vcc
	s_cmp_lt_i32 s94, 32
	v_lshlrev_b32_e32 v125, 2, v4
	v_lshl_add_u64 v[4:5], s[6:7], 0, v[144:145]
	s_cselect_b64 s[6:7], -1, 0
	v_writelane_b32 v255, s6, 22
	s_ashr_i32 s63, s62, 31
	v_lshl_add_u64 v[114:115], v[4:5], 0, v[0:1]
	v_writelane_b32 v255, s7, 23
	s_lshl_b64 s[6:7], s[62:63], 12
	s_add_u32 s0, s30, s6
	s_addc_u32 s6, s31, s7
	v_lshl_add_u64 v[4:5], s[24:25], 0, v[144:145]
	s_add_u32 s24, s0, 0x200000
	s_addc_u32 s25, s6, 0
	v_writelane_b32 v255, s24, 24
	v_cmp_eq_u32_e64 s[6:7], 0, v32
	s_mov_b32 s0, s62
	v_writelane_b32 v255, s25, 25
	v_writelane_b32 v255, s6, 26
	v_lshl_add_u64 v[116:117], v[4:5], 0, v[0:1]
	v_ashrrev_i32_e32 v3, 31, v2
	v_writelane_b32 v255, s7, 27
	v_writelane_b32 v255, s0, 28
	s_lshl_b64 s[6:7], s[62:63], 6
	v_lshlrev_b64 v[2:3], 11, v[2:3]
	v_writelane_b32 v255, s1, 29
	s_add_u32 s0, s4, s6
	s_addc_u32 s13, s5, s7
	s_lshl_b64 s[6:7], s[10:11], 3
	s_add_u32 s0, s0, s6
	v_writelane_b32 v255, s0, 30
	s_addc_u32 s0, s13, s7
	s_cmp_gt_i32 s94, 0
	v_writelane_b32 v255, s0, 31
	s_cselect_b64 s[10:11], -1, 0
	v_writelane_b32 v255, s10, 32
	v_lshl_add_u64 v[2:3], s[30:31], 0, v[2:3]
	v_lshl_add_u64 v[2:3], v[2:3], 0, s[20:21]
	v_writelane_b32 v255, s11, 33
	s_mul_i32 s10, s12, 33
	v_cmp_gt_i32_e64 s[12:13], s94, v32
	s_ashr_i32 s11, s10, 31
	s_lshl_b64 s[92:93], s[10:11], 12
	v_cndmask_b32_e64 v1, 0, v32, s[12:13]
	v_add_u32_e32 v4, s10, v1
	v_ashrrev_i32_e32 v5, 31, v4
	v_lshlrev_b64 v[4:5], 6, v[4:5]
	v_lshl_add_u64 v[4:5], s[4:5], 0, v[4:5]
	s_lshl_b64 s[4:5], s[18:19], 9
	s_add_u32 s4, s4, 0x1188000
	s_addc_u32 s5, s5, 0
	v_writelane_b32 v255, s4, 34
	v_lshl_add_u64 v[2:3], v[2:3], 0, v[6:7]
	v_or_b32_e32 v7, s94, v8
	v_writelane_b32 v255, s5, 35
	s_lshl_b64 s[4:5], s[16:17], 9
	s_add_u32 s4, s4, 0x1100000
	s_addc_u32 s5, s5, 0
	v_writelane_b32 v255, s4, 36
	s_lshl_b32 s0, s88, 7
	s_add_i32 s0, s22, s0
	v_writelane_b32 v255, s5, 37
	s_mov_b64 s[4:5], 0xaf00000
	v_lshl_add_u64 v[120:121], v[2:3], 0, s[4:5]
	v_readlane_b32 s4, v255, 14
	v_lshlrev_b32_e32 v1, 2, v124
	s_addk_i32 s0, 0xff80
	v_cmp_eq_u32_e32 vcc, 0, v7
	v_readlane_b32 s5, v255, 15
	v_lshl_add_u64 v[118:119], v[4:5], 0, s[6:7]
	v_add_u32_e32 v4, s22, v1
	v_add_u32_e32 v126, s0, v1
	v_lshl_add_u32 v1, v11, 2, s22
	s_and_b64 s[22:23], s[4:5], vcc
	s_load_dwordx4 s[4:7], s[2:3], 0xd0
	v_cmp_gt_u32_e64 s[8:9], 32, v32
	s_and_b64 s[18:19], s[14:15], s[8:9]
	v_add_u32_e32 v12, s95, v0
	v_or_b32_e32 v2, 16, v10
	s_waitcnt lgkmcnt(0)
; DI float bf2f(unsigned v) { return __uint_as_float(v << 16); }
; DI float sigmoidf_(float x) { return rcpf(1.f + __expf(-x)); }
; template <bool FINAL>
; DI void lru_unit(KA a, int l, int unit, LAS unsigned char* lds) {
;     ...
; #pragma unroll
;         for (int mb = 0; mb < 2; ++mb) {
;             float pp = 1.f, hh = 0.f;
; #pragma unroll
;             for (int i = 0; i < 16; ++i) {
;                 const int t = 32 * mb + 16 * h + i;
;                 const float rg = sigmoidf_(ar[mb][i] + ba_), ig = sigmoidf_(ai[mb][i] + bx_);
;                 const float la = c8 * rg;
;                 float av = __expf(la), mult = __builtin_amdgcn_sqrtf(fmaxf(1.f - av * av, 0.f));
;                 const float xcv = bf2f(xc[t * 72 + cl]);
;                 float bt = mult * ig * xcv;
;                 if (u.prompt && u.c == 0 && t == 0) { av = 0.f; bt = ig * xcv; }
;                 if (t >= nvalid) { av = 1.f; bt = 0.f; }
;                 hh = av * hh + bt; pp *= av;
;                 ar[mb][i] = pp; ai[mb][i] = hh;
;             }
;         }
	s_add_u32 s0, s6, s92
	s_addc_u32 s4, s7, s93
	s_add_u32 s6, s0, 0x207000
	v_or_b32_e32 v3, 32, v10
	v_or_b32_e32 v5, 48, v10
	v_mul_u32_u24_e32 v6, 0x90, v9
	v_cmp_gt_u32_e64 s[24:25], s88, v0
	v_or_b32_e32 v7, 1, v0
	v_or_b32_e32 v9, 2, v0
	v_or_b32_e32 v11, 3, v0
	v_or_b32_e32 v13, 4, v0
	v_or_b32_e32 v14, 5, v0
	v_or_b32_e32 v15, 6, v0
	v_or_b32_e32 v16, 7, v0
	v_or_b32_e32 v17, 8, v0
	v_or_b32_e32 v18, 9, v0
	v_or_b32_e32 v19, 10, v0
	v_or_b32_e32 v20, 11, v0
	v_or_b32_e32 v21, 12, v0
	v_or_b32_e32 v22, 13, v0
	v_or_b32_e32 v23, 14, v0
	v_or_b32_e32 v24, 15, v0
	v_or_b32_e32 v25, 32, v0
	v_or_b32_e32 v26, 33, v0
	v_or_b32_e32 v27, 34, v0
	v_or_b32_e32 v28, 35, v0
	v_or_b32_e32 v29, 36, v0
	v_or_b32_e32 v30, 37, v0
	v_or_b32_e32 v31, 38, v0
	v_or_b32_e32 v32, 39, v0
	v_or_b32_e32 v33, 40, v0
	v_or_b32_e32 v34, 41, v0
	v_or_b32_e32 v35, 42, v0
	v_or_b32_e32 v36, 43, v0
	v_or_b32_e32 v37, 44, v0
	v_or_b32_e32 v38, 45, v0
	v_or_b32_e32 v39, 46, v0
	v_or_b32_e32 v0, 47, v0
	s_addc_u32 s7, s4, 0
	v_cmp_gt_u32_e64 s[14:15], s88, v10
	v_cmp_gt_u32_e64 s[10:11], s88, v2
	v_cmp_gt_u32_e64 s[96:97], s88, v3
	v_cmp_gt_u32_e64 s[20:21], s88, v5
	v_mul_u32_u24_e32 v127, 0x900, v8
	v_mul_u32_u24_e32 v128, 0x90, v7
	v_cmp_gt_u32_e64 s[26:27], s88, v7
	v_cmp_gt_u32_e64 s[28:29], s88, v9
	v_cmp_gt_u32_e64 s[30:31], s88, v11
	v_cmp_gt_u32_e64 s[34:35], s88, v13
	v_cmp_gt_u32_e64 s[36:37], s88, v14
	v_cmp_gt_u32_e64 s[38:39], s88, v15
	v_cmp_gt_u32_e64 s[40:41], s88, v16
	v_cmp_gt_u32_e64 s[42:43], s88, v17
	v_cmp_gt_u32_e64 s[44:45], s88, v18
	v_cmp_gt_u32_e64 s[46:47], s88, v19
	v_cmp_gt_u32_e64 s[48:49], s88, v20
	v_cmp_gt_u32_e64 s[50:51], s88, v21
	v_cmp_gt_u32_e64 s[52:53], s88, v22
	v_cmp_gt_u32_e64 s[54:55], s88, v23
	v_cmp_gt_u32_e64 s[56:57], s88, v24
	v_cmp_gt_u32_e64 s[58:59], s88, v25
	v_cmp_gt_u32_e64 s[60:61], s88, v26
	v_cmp_gt_u32_e64 s[62:63], s88, v27
	v_cmp_gt_u32_e64 s[64:65], s88, v28
	v_cmp_gt_u32_e64 s[66:67], s88, v29
	v_cmp_gt_u32_e64 s[68:69], s88, v30
	v_cmp_gt_u32_e64 s[70:71], s88, v31
	v_cmp_gt_u32_e64 s[72:73], s88, v32
	v_cmp_gt_u32_e64 s[74:75], s88, v33
	v_cmp_gt_u32_e64 s[76:77], s88, v34
	v_cmp_gt_u32_e64 s[78:79], s88, v35
	v_cmp_gt_u32_e64 s[80:81], s88, v36
	v_cmp_gt_u32_e64 s[82:83], s88, v37
	v_cmp_gt_u32_e64 s[84:85], s88, v38
	v_cmp_gt_u32_e64 s[86:87], s88, v39
	v_cmp_gt_u32_e64 s[88:89], s88, v0
	v_lshlrev_b32_e32 v8, 11, v8
	v_lshlrev_b32_e32 v7, 7, v7
	v_lshlrev_b32_e32 v9, 7, v9
	v_lshlrev_b32_e32 v11, 7, v11
	v_lshlrev_b32_e32 v13, 7, v13
	v_lshlrev_b32_e32 v14, 7, v14
	v_lshlrev_b32_e32 v15, 7, v15
	v_lshlrev_b32_e32 v16, 7, v16
	v_lshlrev_b32_e32 v17, 7, v17
	v_lshlrev_b32_e32 v18, 7, v18
	v_lshlrev_b32_e32 v19, 7, v19
	v_lshlrev_b32_e32 v20, 7, v20
	v_lshlrev_b32_e32 v21, 7, v21
	v_lshlrev_b32_e32 v22, 7, v22
	v_lshlrev_b32_e32 v23, 7, v23
	v_lshlrev_b32_e32 v24, 7, v24
	v_lshlrev_b32_e32 v25, 7, v25
	v_lshlrev_b32_e32 v26, 7, v26
	v_lshlrev_b32_e32 v27, 7, v27
	v_lshlrev_b32_e32 v28, 7, v28
	v_lshlrev_b32_e32 v29, 7, v29
	v_lshlrev_b32_e32 v30, 7, v30
	v_lshlrev_b32_e32 v31, 7, v31
	v_lshlrev_b32_e32 v32, 7, v32
	v_lshlrev_b32_e32 v33, 7, v33
	v_lshlrev_b32_e32 v34, 7, v34
	v_lshlrev_b32_e32 v35, 7, v35
	v_lshlrev_b32_e32 v36, 7, v36
	v_lshlrev_b32_e32 v37, 7, v37
	v_lshlrev_b32_e32 v38, 7, v38
	v_lshlrev_b32_e32 v39, 7, v39
	v_lshlrev_b32_e32 v0, 7, v0
	v_lshlrev_b32_e32 v10, 7, v10
	v_lshlrev_b32_e32 v2, 7, v2
	v_lshlrev_b32_e32 v3, 7, v3
	v_lshlrev_b32_e32 v5, 7, v5
	v_writelane_b32 v255, s6, 38
	s_mov_b32 s90, 0
	s_mov_b64 s[92:93], -1
	v_writelane_b32 v255, s7, 39
	v_add_u32_e32 v129, v12, v6
	v_add_u32_e32 v130, v4, v8
	v_add_u32_e32 v131, v4, v7
	v_add_u32_e32 v132, v4, v9
	v_add_u32_e32 v133, v4, v11
	v_add_u32_e32 v134, v4, v13
	v_add_u32_e32 v135, v4, v14
	v_add_u32_e32 v136, v4, v15
	v_add_u32_e32 v137, v4, v16
	v_add_u32_e32 v138, v4, v17
	v_add_u32_e32 v139, v4, v18
	v_add_u32_e32 v140, v4, v19
	v_add_u32_e32 v141, v4, v20
	v_add_u32_e32 v142, v4, v21
	v_add_u32_e32 v143, v4, v22
	v_add_u32_e32 v144, v4, v23
	v_add_u32_e32 v154, v4, v24
	v_add_u32_e32 v155, v4, v25
	v_add_u32_e32 v156, v4, v26
	v_add_u32_e32 v157, v4, v27
	v_add_u32_e32 v158, v4, v28
	v_add_u32_e32 v159, v4, v29
	v_add_u32_e32 v160, v4, v30
	v_add_u32_e32 v161, v4, v31
	v_add_u32_e32 v162, v4, v32
	v_add_u32_e32 v163, v4, v33
	v_add_u32_e32 v164, v4, v34
	v_add_u32_e32 v165, v4, v35
	v_add_u32_e32 v166, v4, v36
	v_add_u32_e32 v167, v4, v37
	v_add_u32_e32 v168, v4, v38
	v_add_u32_e32 v169, v4, v39
	v_add_u32_e32 v170, v4, v0
	v_add_u32_e32 v171, v1, v10
	v_add_u32_e32 v172, v1, v2
	v_add_u32_e32 v173, v1, v3
	v_add_u32_e32 v174, v1, v5
	s_branch .LBB0_1003
